# S5 item loops: per-item workgroup barrier and top-of-trip vmcnt(0) removed (wave-private items), one wait in front of the loop
# baseline (speedup 1.0000x reference)
.LBB0_826:
	s_or_b64 exec, exec, s[2:3]
	s_waitcnt vmcnt(0)
	s_and_saveexec_b64 s[2:3], vcc
	v_cvt_pk_bf16_f32 v24, v164, s0
	v_cvt_pk_bf16_f32 v20, v165, s0
	v_cvt_pk_bf16_f32 v30, v166, s0
	v_cvt_pk_bf16_f32 v25, v167, s0
	v_cvt_pk_bf16_f32 v31, v170, s0
	v_cvt_pk_bf16_f32 v21, v171, s0
	v_cvt_pk_bf16_f32 v32, v172, s0
	v_cvt_pk_bf16_f32 v26, v173, s0
	v_cvt_pk_bf16_f32 v33, v174, s0
	v_cvt_pk_bf16_f32 v22, v175, s0
	v_cvt_pk_bf16_f32 v34, v176, s0
	v_cvt_pk_bf16_f32 v27, v177, s0
	v_cvt_pk_bf16_f32 v35, v178, s0
	v_cvt_pk_bf16_f32 v23, v179, s0
	v_cvt_pk_bf16_f32 v36, v180, s0
	v_cvt_pk_bf16_f32 v37, v181, s0
	v_cvt_pk_bf16_f32 v16, v182, s0
	v_cvt_pk_bf16_f32 v12, v183, s0
	v_cvt_pk_bf16_f32 v38, v184, s0
	v_cvt_pk_bf16_f32 v17, v185, s0
	v_cvt_pk_bf16_f32 v39, v186, s0
	v_cvt_pk_bf16_f32 v18, v187, s0
	v_cvt_pk_bf16_f32 v40, v190, s0
	v_cvt_pk_bf16_f32 v19, v191, s0
	v_cvt_pk_bf16_f32 v41, v192, s0
	v_cvt_pk_bf16_f32 v14, v193, s0
	v_cvt_pk_bf16_f32 v42, v198, s0
	v_cvt_pk_bf16_f32 v43, v199, s0
	v_cvt_pk_bf16_f32 v44, v200, s0
	v_cvt_pk_bf16_f32 v15, v201, s0
	v_cvt_pk_bf16_f32 v45, v202, s0
	v_cvt_pk_bf16_f32 v46, v203, s0
	v_cvt_pk_bf16_f32 v47, v204, s0
	v_cvt_pk_bf16_f32 v56, v205, s0
	v_cvt_pk_bf16_f32 v57, v206, s0
	v_cvt_pk_bf16_f32 v62, v207, s0
	v_cvt_pk_bf16_f32 v68, v208, s0
	v_cvt_pk_bf16_f32 v70, v209, s0
	v_cvt_pk_bf16_f32 v73, v210, s0
	v_cvt_pk_bf16_f32 v74, v211, s0
	v_cvt_pk_bf16_f32 v77, v212, s0
	v_cvt_pk_bf16_f32 v78, v213, s0
	v_cvt_pk_bf16_f32 v81, v214, s0
	v_cvt_pk_bf16_f32 v82, v215, s0
	v_cvt_pk_bf16_f32 v85, v216, s0
	v_cvt_pk_bf16_f32 v86, v217, s0
	v_cvt_pk_bf16_f32 v87, v218, s0
	v_cvt_pk_bf16_f32 v88, v219, s0
	v_cvt_pk_bf16_f32 v58, v220, s0
	v_cvt_pk_bf16_f32 v59, v221, s0
	v_cvt_pk_bf16_f32 v63, v222, s0
	v_cvt_pk_bf16_f32 v64, v223, s0
	v_cvt_pk_bf16_f32 v65, v224, s0
	v_cvt_pk_bf16_f32 v66, v225, s0
	v_cvt_pk_bf16_f32 v67, v226, s0
	v_cvt_pk_bf16_f32 v69, v227, s0
	v_cvt_pk_bf16_f32 v71, v228, s0
	v_cvt_pk_bf16_f32 v72, v229, s0
	v_cvt_pk_bf16_f32 v75, v230, s0
	v_cvt_pk_bf16_f32 v76, v231, s0
	v_cvt_pk_bf16_f32 v79, v232, s0
	v_cvt_pk_bf16_f32 v80, v233, s0
	v_cvt_pk_bf16_f32 v83, v234, s0
	v_cvt_pk_bf16_f32 v84, v235, s0
	s_or_b64 exec, exec, s[2:3]
	v_ashrrev_i32_e32 v0, 5, v29
	s_mov_b32 s2, 0xfe03f81
	s_mov_b32 s4, 0x5040100
	v_mul_hi_i32 v1, v0, s2
	v_perm_b32 v24, v30, v24, s4
	v_lshrrev_b32_e32 v30, 31, v1
	v_ashrrev_i32_e32 v1, 4, v1
	v_add_u32_e32 v30, v1, v30
	v_mul_i32_i24_e32 v1, 0x102, v30
	v_sub_u32_e32 v0, v0, v1
	v_ashrrev_i32_e32 v1, 31, v0
	v_mul_i32_i24_e32 v30, 0x4080, v30
	v_perm_b32 v20, v25, v20, s4
	v_perm_b32 v25, v32, v31, s4
	v_lshlrev_b64 v[0:1], 6, v[0:1]
	v_ashrrev_i32_e32 v31, 31, v30
	v_mov_b32_e32 v32, v160
	v_lshl_add_u64 v[0:1], v[0:1], 0, v[30:31]
	v_perm_b32 v8, v57, v47, s4
	v_and_or_b32 v0, v32, 63, v0
	v_mad_u64_u32 v[30:31], s[2:3], v0, s97, v[48:49]
	v_lshlrev_b32_e32 v0, 5, v29
	v_mad_i32_i24 v31, v1, s97, v31
	v_and_b32_e32 v162, 0x3e0, v0
	v_lshl_add_u64 v[0:1], v[30:31], 0, v[162:163]
	v_perm_b32 v15, v46, v15, s4
	v_perm_b32 v14, v43, v14, s4
	v_perm_b32 v13, v19, v18, s4
	v_perm_b32 v12, v17, v12, s4
	v_perm_b32 v19, v45, v44, s4
	v_perm_b32 v18, v42, v41, s4
	v_perm_b32 v17, v40, v39, s4
	global_load_dwordx4 v[40:43], v[0:1], off offset:3600
	global_load_dwordx4 v[44:47], v[0:1], off offset:3584
	s_movk_i32 s2, 0x3300
	v_mul_lo_u32 v0, v28, s2
	s_mov_b64 s[2:3], 0x1e422000
	v_perm_b32 v7, v88, v86, s4
	v_perm_b32 v6, v82, v78, s4
	v_perm_b32 v5, v74, v70, s4
	v_perm_b32 v4, v62, v56, s4
	v_perm_b32 v11, v87, v85, s4
	v_perm_b32 v10, v81, v77, s4
	v_perm_b32 v9, v73, v68, s4
	v_perm_b32 v16, v38, v16, s4
	v_perm_b32 v23, v37, v23, s4
	v_perm_b32 v22, v27, v22, s4
	v_perm_b32 v21, v26, v21, s4
	v_perm_b32 v27, v36, v35, s4
	v_perm_b32 v26, v34, v33, s4
	v_add_u32_e32 v62, 0x100, v0
	v_lshl_add_u64 v[56:57], v[2:3], 0, s[2:3]
	v_perm_b32 v28, v64, v59, s4
	v_perm_b32 v29, v69, v66, s4
	v_perm_b32 v30, v76, v72, s4
	v_perm_b32 v31, v84, v80, s4
	v_perm_b32 v0, v63, v58, s4
	v_perm_b32 v1, v67, v65, s4
	v_perm_b32 v2, v75, v71, s4
	v_perm_b32 v3, v83, v79, s4
	s_waitcnt vmcnt(0)

.LBB0_957:
	s_or_b64 exec, exec, s[2:3]
	v_readlane_b32 s2, v253, 1
	v_readlane_b32 s3, v253, 2
	s_load_dword s2, s[2:3], 0x0
	v_mov_b64_e32 v[32:33], v[40:41]
	v_mov_b64_e32 v[36:37], v[44:45]
	v_mov_b64_e32 v[34:35], v[42:43]
	v_mov_b64_e32 v[38:39], v[46:47]
	s_waitcnt lgkmcnt(0)
	s_add_i32 s10, s2, s10
	s_add_i32 s10, s10, -16
	s_cmpk_gt_i32 s10, 0x101f
	s_cselect_b64 s[2:3], -1, 0
	s_and_b64 vcc, exec, s[2:3]
	s_cbranch_vccnz .LBB0_959
	v_lshl_add_u32 v36, s10, 3, v60
	v_ashrrev_i32_e32 v32, 5, v36
	s_mov_b32 s4, 0xfe03f81
	v_mul_hi_i32 v33, v32, s4
	v_lshrrev_b32_e32 v34, 31, v33
	v_ashrrev_i32_e32 v33, 4, v33
	v_add_u32_e32 v33, v33, v34
	v_mul_i32_i24_e32 v34, 0x102, v33
	v_sub_u32_e32 v32, v32, v34
	v_mul_hi_i32_i24_e32 v35, 0x4080, v33
	v_mul_i32_i24_e32 v34, 0x4080, v33
	v_ashrrev_i32_e32 v33, 31, v32
	v_lshlrev_b64 v[32:33], 6, v[32:33]
	v_mov_b32_e32 v37, v160
	v_lshl_add_u64 v[32:33], v[34:35], 0, v[32:33]
	s_nop 0
	v_and_or_b32 v32, v37, 63, v32
	v_mad_u64_u32 v[34:35], s[4:5], v32, s97, v[48:49]
	v_mov_b32_e32 v32, v35
	v_mad_u64_u32 v[32:33], s[4:5], v33, s97, v[32:33]
	v_mov_b32_e32 v35, v32
	v_lshlrev_b32_e32 v32, 5, v36
	v_and_b32_e32 v162, 0x3e0, v32
	v_lshl_add_u64 v[36:37], v[34:35], 0, v[162:163]
	global_load_dwordx4 v[32:35], v[36:37], off offset:3600
	s_nop 0
	global_load_dwordx4 v[36:39], v[36:37], off offset:3584

.LBB0_960:
	v_add_u32_e32 v66, s4, v59
	ds_read_b128 v[66:69], v66
	v_add_u32_e32 v82, 0x1000, v64
	v_add_u32_e32 v83, 0x1800, v64
	s_addk_i32 s4, 0x400
	s_cmpk_lg_i32 s4, 0x1000
	s_waitcnt lgkmcnt(0)
	v_mfma_f32_16x16x32_bf16 v[70:73], v[24:27], v[66:69], 0
	v_mfma_f32_16x16x32_bf16 v[74:77], v[20:23], v[66:69], 0
	s_nop 6
	v_cvt_pk_bf16_f32 v78, v70, v71
	v_cvt_pk_bf16_f32 v79, v72, v73
	v_cvt_pk_bf16_f32 v80, v74, v75
	v_cvt_pk_bf16_f32 v81, v76, v77
	v_mfma_f32_16x16x32_bf16 v[70:73], v[16:19], v[66:69], 0
	v_mfma_f32_16x16x32_bf16 v[74:77], v[12:15], v[66:69], 0
	s_nop 6
	v_cvt_pk_bf16_f32 v70, v70, v71
	v_cvt_pk_bf16_f32 v71, v72, v73
	v_cvt_pk_bf16_f32 v72, v74, v75
	v_cvt_pk_bf16_f32 v73, v76, v77
	ds_write2_b64 v82, v[78:79], v[70:71] offset1:4
	ds_write2_b64 v83, v[80:81], v[72:73] offset0:32 offset1:36
	v_mfma_f32_16x16x32_bf16 v[70:73], v[8:11], v[66:69], 0
	v_mfma_f32_16x16x32_bf16 v[74:77], v[4:7], v[66:69], 0
	s_nop 6
	v_cvt_pk_bf16_f32 v78, v70, v71
	v_cvt_pk_bf16_f32 v79, v72, v73
	v_mfma_f32_16x16x32_bf16 v[70:73], v[0:3], v[66:69], 0
	v_cvt_pk_bf16_f32 v74, v74, v75
	v_cvt_pk_bf16_f32 v75, v76, v77
	v_mfma_f32_16x16x32_bf16 v[66:69], v[28:31], v[66:69], 0
	s_nop 4
	v_cvt_pk_bf16_f32 v70, v70, v71
	v_cvt_pk_bf16_f32 v71, v72, v73
	s_nop 0
	v_cvt_pk_bf16_f32 v66, v66, v67
	v_cvt_pk_bf16_f32 v67, v68, v69
	ds_write2_b64 v82, v[78:79], v[70:71] offset0:8 offset1:12
	ds_write2_b64 v83, v[74:75], v[66:67] offset0:40 offset1:44
	s_waitcnt lgkmcnt(0)
	ds_read_u16 v66, v65 offset:4096
	s_waitcnt lgkmcnt(0)
	v_lshlrev_b32_e32 v68, 16, v66
	ds_read_u16 v66, v65 offset:6400
	s_waitcnt lgkmcnt(0)
	v_lshlrev_b32_e32 v69, 16, v66
	v_pk_mul_f32 v[66:67], v[54:55], v[46:47]
	v_pk_mul_f32 v[46:47], v[44:45], v[46:47]
	v_sub_f32_e32 v66, v66, v67
	v_add_f32_e32 v46, v46, v47
	ds_read_u16 v47, v65 offset:4240
	v_add_f32_e32 v46, v46, v69
	v_add_f32_e32 v66, v66, v68
	s_waitcnt lgkmcnt(0)
	v_lshlrev_b32_e32 v69, 16, v47
	ds_read_u16 v47, v65 offset:6544
	s_waitcnt lgkmcnt(0)
	v_lshlrev_b32_e32 v68, 16, v47
	v_pk_mul_f32 v[46:47], v[54:55], v[46:47] op_sel_hi:[1,0]
	s_nop 0
	v_pk_fma_f32 v[70:71], v[44:45], v[66:67], v[46:47]
	v_pk_fma_f32 v[46:47], v[44:45], v[66:67], v[46:47] op_sel_hi:[1,0,1] neg_lo:[0,0,1] neg_hi:[0,0,1]
	ds_read_u16 v46, v65 offset:4816
	v_mov_b32_e32 v71, v47
	ds_read_u16 v47, v65 offset:7120
	v_pk_add_f32 v[66:67], v[70:71], v[68:69]
	ds_read_u16 v68, v65 offset:6688
	ds_read_u16 v69, v65 offset:4384
	v_pk_mul_f32 v[70:71], v[42:43], v[66:67]
	s_waitcnt lgkmcnt(3)
	v_lshlrev_b32_e32 v46, 16, v46
	v_pk_fma_f32 v[72:73], v[40:41], v[66:67], v[70:71] op_sel:[0,0,1] op_sel_hi:[1,1,0]
	v_pk_fma_f32 v[66:67], v[40:41], v[66:67], v[70:71] op_sel:[0,0,1] op_sel_hi:[1,1,0] neg_lo:[0,0,1] neg_hi:[0,0,1]
	s_waitcnt lgkmcnt(0)
	v_lshlrev_b32_e32 v69, 16, v69
	v_lshlrev_b32_e32 v68, 16, v68
	v_mov_b32_e32 v73, v67
	v_pk_add_f32 v[66:67], v[72:73], v[68:69]
	ds_read_u16 v68, v65 offset:6832
	ds_read_u16 v69, v65 offset:4528
	v_pk_mul_f32 v[70:71], v[42:43], v[66:67]
	v_lshlrev_b32_e32 v47, 16, v47
	v_pk_fma_f32 v[72:73], v[40:41], v[66:67], v[70:71] op_sel:[0,0,1] op_sel_hi:[1,1,0]
	v_pk_fma_f32 v[66:67], v[40:41], v[66:67], v[70:71] op_sel:[0,0,1] op_sel_hi:[1,1,0] neg_lo:[0,0,1] neg_hi:[0,0,1]
	s_waitcnt lgkmcnt(0)
	v_lshlrev_b32_e32 v69, 16, v69
	v_lshlrev_b32_e32 v68, 16, v68
	v_mov_b32_e32 v73, v67
	v_pk_add_f32 v[66:67], v[72:73], v[68:69]
	ds_read_u16 v68, v65 offset:6976
	ds_read_u16 v69, v65 offset:4672
	v_pk_mul_f32 v[70:71], v[42:43], v[66:67]
	s_waitcnt lgkmcnt(1)
	v_lshlrev_b32_e32 v68, 16, v68
	v_pk_fma_f32 v[72:73], v[40:41], v[66:67], v[70:71] op_sel:[0,0,1] op_sel_hi:[1,1,0]
	v_pk_fma_f32 v[66:67], v[40:41], v[66:67], v[70:71] op_sel:[0,0,1] op_sel_hi:[1,1,0] neg_lo:[0,0,1] neg_hi:[0,0,1]
	s_waitcnt lgkmcnt(0)
	v_lshlrev_b32_e32 v69, 16, v69
	v_mov_b32_e32 v73, v67
	v_pk_add_f32 v[66:67], v[72:73], v[68:69]
	s_nop 0
	v_mul_f32_e32 v68, v55, v66
	v_mul_f32_e32 v70, v54, v66
	v_pk_fma_f32 v[68:69], v[54:55], v[66:67], v[68:69] op_sel:[0,1,0] op_sel_hi:[1,0,0] neg_lo:[0,0,1] neg_hi:[0,0,1]
	v_pk_fma_f32 v[66:67], v[54:55], v[66:67], v[70:71] op_sel_hi:[1,1,0]
	s_nop 0
	v_mov_b32_e32 v69, v67
	ds_read_u16 v66, v65 offset:4960
	ds_read_u16 v67, v65 offset:7264
	v_pk_add_f32 v[46:47], v[68:69], v[46:47]
	s_waitcnt lgkmcnt(1)
	v_lshlrev_b32_e32 v66, 16, v66
	v_pk_mul_f32 v[68:69], v[42:43], v[46:47]
	s_waitcnt lgkmcnt(0)
	v_lshlrev_b32_e32 v67, 16, v67
	v_pk_fma_f32 v[70:71], v[40:41], v[46:47], v[68:69] op_sel:[0,0,1] op_sel_hi:[1,1,0] neg_lo:[0,0,1] neg_hi:[0,0,1]
	v_pk_fma_f32 v[46:47], v[40:41], v[46:47], v[68:69] op_sel:[0,0,1] op_sel_hi:[1,1,0]
	s_nop 0
	v_mov_b32_e32 v71, v47
	v_pk_add_f32 v[46:47], v[70:71], v[66:67]
	ds_read_u16 v66, v65 offset:5104
	ds_read_u16 v67, v65 offset:7408
	v_pk_mul_f32 v[68:69], v[42:43], v[46:47]
	s_waitcnt lgkmcnt(1)
	v_lshlrev_b32_e32 v66, 16, v66
	v_pk_fma_f32 v[70:71], v[40:41], v[46:47], v[68:69] op_sel:[0,0,1] op_sel_hi:[1,1,0] neg_lo:[0,0,1] neg_hi:[0,0,1]
	v_pk_fma_f32 v[46:47], v[40:41], v[46:47], v[68:69] op_sel:[0,0,1] op_sel_hi:[1,1,0]
	s_waitcnt lgkmcnt(0)
	v_lshlrev_b32_e32 v67, 16, v67
	v_mov_b32_e32 v71, v47
	v_pk_add_f32 v[46:47], v[70:71], v[66:67]
	ds_read_u16 v66, v65 offset:5248
	ds_read_u16 v67, v65 offset:7552
	v_pk_mul_f32 v[68:69], v[42:43], v[46:47]
	s_waitcnt lgkmcnt(1)
	v_lshlrev_b32_e32 v66, 16, v66
	v_pk_fma_f32 v[70:71], v[40:41], v[46:47], v[68:69] op_sel:[0,0,1] op_sel_hi:[1,1,0] neg_lo:[0,0,1] neg_hi:[0,0,1]
	v_pk_fma_f32 v[46:47], v[40:41], v[46:47], v[68:69] op_sel:[0,0,1] op_sel_hi:[1,1,0]
	s_waitcnt lgkmcnt(0)
	v_lshlrev_b32_e32 v67, 16, v67
	v_mov_b32_e32 v71, v47
	v_pk_add_f32 v[46:47], v[70:71], v[66:67]
	ds_read_u16 v68, v65 offset:5392
	ds_read_u16 v69, v65 offset:7696
	ds_read_u16 v66, v65 offset:5824
	v_pk_mul_f32 v[70:71], v[42:43], v[46:47]
	ds_read_u16 v67, v65 offset:8128
	v_pk_fma_f32 v[72:73], v[40:41], v[46:47], v[70:71] op_sel:[0,0,1] op_sel_hi:[1,1,0] neg_lo:[0,0,1] neg_hi:[0,0,1]
	v_pk_fma_f32 v[46:47], v[40:41], v[46:47], v[70:71] op_sel:[0,0,1] op_sel_hi:[1,1,0]
	s_waitcnt lgkmcnt(2)
	v_lshlrev_b32_e32 v69, 16, v69
	v_lshlrev_b32_e32 v68, 16, v68
	v_mov_b32_e32 v73, v47
	v_pk_add_f32 v[46:47], v[72:73], v[68:69]
	ds_read_u16 v68, v65 offset:5536
	ds_read_u16 v69, v65 offset:7840
	v_pk_mul_f32 v[70:71], v[42:43], v[46:47]
	s_waitcnt lgkmcnt(3)
	v_lshlrev_b32_e32 v66, 16, v66
	v_pk_fma_f32 v[72:73], v[40:41], v[46:47], v[70:71] op_sel:[0,0,1] op_sel_hi:[1,1,0] neg_lo:[0,0,1] neg_hi:[0,0,1]
	v_pk_fma_f32 v[46:47], v[40:41], v[46:47], v[70:71] op_sel:[0,0,1] op_sel_hi:[1,1,0]
	s_waitcnt lgkmcnt(0)
	v_lshlrev_b32_e32 v69, 16, v69
	v_lshlrev_b32_e32 v68, 16, v68
	v_mov_b32_e32 v73, v47
	v_pk_add_f32 v[46:47], v[72:73], v[68:69]
	ds_read_u16 v68, v65 offset:5680
	ds_read_u16 v69, v65 offset:7984
	v_pk_mul_f32 v[70:71], v[42:43], v[46:47]
	v_lshlrev_b32_e32 v67, 16, v67
	v_pk_fma_f32 v[72:73], v[40:41], v[46:47], v[70:71] op_sel:[0,0,1] op_sel_hi:[1,1,0] neg_lo:[0,0,1] neg_hi:[0,0,1]
	v_pk_fma_f32 v[46:47], v[40:41], v[46:47], v[70:71] op_sel:[0,0,1] op_sel_hi:[1,1,0]
	s_waitcnt lgkmcnt(0)
	v_lshlrev_b32_e32 v69, 16, v69
	v_lshlrev_b32_e32 v68, 16, v68
	v_mov_b32_e32 v73, v47
	v_pk_add_f32 v[46:47], v[72:73], v[68:69]
	s_nop 0
	v_pk_mul_f32 v[68:69], v[42:43], v[46:47]
	s_nop 0
	v_pk_fma_f32 v[70:71], v[40:41], v[46:47], v[68:69] op_sel:[0,0,1] op_sel_hi:[1,1,0] neg_lo:[0,0,1] neg_hi:[0,0,1]
	v_pk_fma_f32 v[46:47], v[40:41], v[46:47], v[68:69] op_sel:[0,0,1] op_sel_hi:[1,1,0]
	s_nop 0
	v_mov_b32_e32 v71, v47
	v_pk_add_f32 v[46:47], v[70:71], v[66:67]
	ds_read_u16 v66, v65 offset:5968
	ds_read_u16 v67, v65 offset:8272
	v_pk_mul_f32 v[68:69], v[42:43], v[46:47]
	s_waitcnt lgkmcnt(1)
	v_lshlrev_b32_e32 v66, 16, v66
	v_pk_fma_f32 v[70:71], v[40:41], v[46:47], v[68:69] op_sel:[0,0,1] op_sel_hi:[1,1,0] neg_lo:[0,0,1] neg_hi:[0,0,1]
	v_pk_fma_f32 v[46:47], v[40:41], v[46:47], v[68:69] op_sel:[0,0,1] op_sel_hi:[1,1,0]
	s_waitcnt lgkmcnt(0)
	v_lshlrev_b32_e32 v67, 16, v67
	v_mov_b32_e32 v71, v47
	v_pk_add_f32 v[46:47], v[70:71], v[66:67]
	ds_read_u16 v66, v65 offset:6112
	ds_read_u16 v67, v65 offset:8416
	v_pk_mul_f32 v[68:69], v[42:43], v[46:47]
	s_waitcnt lgkmcnt(1)
	v_lshlrev_b32_e32 v66, 16, v66
	v_pk_fma_f32 v[70:71], v[40:41], v[46:47], v[68:69] op_sel:[0,0,1] op_sel_hi:[1,1,0] neg_lo:[0,0,1] neg_hi:[0,0,1]
	v_pk_fma_f32 v[46:47], v[40:41], v[46:47], v[68:69] op_sel:[0,0,1] op_sel_hi:[1,1,0]
	s_waitcnt lgkmcnt(0)
	v_lshlrev_b32_e32 v67, 16, v67
	v_mov_b32_e32 v71, v47
	v_pk_add_f32 v[46:47], v[70:71], v[66:67]
	ds_read_u16 v66, v65 offset:6256
	ds_read_u16 v67, v65 offset:8560
	v_pk_mul_f32 v[68:69], v[42:43], v[46:47]
	s_waitcnt lgkmcnt(0)
	s_waitcnt lgkmcnt(1)
	v_lshlrev_b32_e32 v66, 16, v66
	v_pk_fma_f32 v[70:71], v[40:41], v[46:47], v[68:69] op_sel:[0,0,1] op_sel_hi:[1,1,0] neg_lo:[0,0,1] neg_hi:[0,0,1]
	v_pk_fma_f32 v[46:47], v[40:41], v[46:47], v[68:69] op_sel:[0,0,1] op_sel_hi:[1,1,0]
	s_waitcnt lgkmcnt(0)
	v_lshlrev_b32_e32 v67, 16, v67
	v_mov_b32_e32 v71, v47
	v_pk_add_f32 v[46:47], v[70:71], v[66:67]
	s_cbranch_scc1 .LBB0_960
	v_ashrrev_i32_e32 v59, 31, v58
	v_lshlrev_b64 v[40:41], 9, v[58:59]
	v_lshl_add_u64 v[40:41], v[56:57], 0, v[40:41]
	v_lshlrev_b32_e32 v162, 3, v63
	v_lshl_add_u64 v[40:41], v[40:41], 0, v[162:163]
	global_store_dwordx2 v[40:41], v[46:47], off
	s_waitcnt vmcnt(1)
	v_mov_b64_e32 v[46:47], v[38:39]
	v_mov_b64_e32 v[42:43], v[34:35]
	s_andn2_b64 vcc, exec, s[2:3]
	v_mov_b64_e32 v[44:45], v[36:37]
	v_mov_b64_e32 v[40:41], v[32:33]
	s_cbranch_vccnz .LBB0_827

.LBB0_1239:
	s_or_b64 exec, exec, s[2:3]
	s_waitcnt vmcnt(0)
	s_and_saveexec_b64 s[2:3], vcc
	v_cvt_pk_bf16_f32 v28, v164, s0
	v_cvt_pk_bf16_f32 v24, v165, s0
	v_cvt_pk_bf16_f32 v36, v166, s0
	v_cvt_pk_bf16_f32 v29, v167, s0
	v_cvt_pk_bf16_f32 v37, v170, s0
	v_cvt_pk_bf16_f32 v25, v171, s0
	v_cvt_pk_bf16_f32 v38, v172, s0
	v_cvt_pk_bf16_f32 v30, v173, s0
	v_cvt_pk_bf16_f32 v39, v174, s0
	v_cvt_pk_bf16_f32 v26, v175, s0
	v_cvt_pk_bf16_f32 v40, v176, s0
	v_cvt_pk_bf16_f32 v31, v177, s0
	v_cvt_pk_bf16_f32 v41, v178, s0
	v_cvt_pk_bf16_f32 v27, v179, s0
	v_cvt_pk_bf16_f32 v42, v180, s0
	v_cvt_pk_bf16_f32 v43, v181, s0
	v_cvt_pk_bf16_f32 v20, v182, s0
	v_cvt_pk_bf16_f32 v21, v183, s0
	v_cvt_pk_bf16_f32 v45, v184, s0
	v_cvt_pk_bf16_f32 v22, v185, s0
	v_cvt_pk_bf16_f32 v46, v186, s0
	v_cvt_pk_bf16_f32 v23, v187, s0
	v_cvt_pk_bf16_f32 v47, v190, s0
	v_cvt_pk_bf16_f32 v48, v191, s0
	v_cvt_pk_bf16_f32 v49, v192, s0
	v_cvt_pk_bf16_f32 v50, v193, s0
	v_cvt_pk_bf16_f32 v51, v198, s0
	v_cvt_pk_bf16_f32 v64, v199, s0
	v_cvt_pk_bf16_f32 v65, v200, s0
	v_cvt_pk_bf16_f32 v19, v201, s0
	v_cvt_pk_bf16_f32 v66, v202, s0
	v_cvt_pk_bf16_f32 v67, v203, s0
	v_cvt_pk_bf16_f32 v68, v204, s0
	v_cvt_pk_bf16_f32 v69, v205, s0
	v_cvt_pk_bf16_f32 v70, v206, s0
	v_cvt_pk_bf16_f32 v71, v207, s0
	v_cvt_pk_bf16_f32 v78, v208, s0
	v_cvt_pk_bf16_f32 v79, v209, s0
	v_cvt_pk_bf16_f32 v90, v210, s0
	v_cvt_pk_bf16_f32 v91, v211, s0
	v_cvt_pk_bf16_f32 v92, v212, s0
	v_cvt_pk_bf16_f32 v93, v213, s0
	v_cvt_pk_bf16_f32 v94, v214, s0
	v_cvt_pk_bf16_f32 v95, v215, s0
	v_cvt_pk_bf16_f32 v97, v216, s0
	v_cvt_pk_bf16_f32 v98, v217, s0
	v_cvt_pk_bf16_f32 v99, v218, s0
	v_cvt_pk_bf16_f32 v100, v219, s0
	v_cvt_pk_bf16_f32 v56, v220, s0
	v_cvt_pk_bf16_f32 v52, v221, s0
	v_cvt_pk_bf16_f32 v57, v222, s0
	v_cvt_pk_bf16_f32 v53, v223, s0
	v_cvt_pk_bf16_f32 v58, v224, s0
	v_cvt_pk_bf16_f32 v54, v225, s0
	v_cvt_pk_bf16_f32 v59, v226, s0
	v_cvt_pk_bf16_f32 v55, v227, s0
	v_cvt_pk_bf16_f32 v60, v228, s0
	v_cvt_pk_bf16_f32 v61, v229, s0
	v_cvt_pk_bf16_f32 v62, v230, s0
	v_cvt_pk_bf16_f32 v63, v231, s0
	v_cvt_pk_bf16_f32 v84, v232, s0
	v_cvt_pk_bf16_f32 v85, v233, s0
	v_cvt_pk_bf16_f32 v86, v234, s0
	v_cvt_pk_bf16_f32 v87, v235, s0
	s_or_b64 exec, exec, s[2:3]
	v_readlane_b32 s2, v255, 24
	s_mov_b32 s4, 0x5040100
	s_lshl_b32 s8, s2, 5
	v_perm_b32 v28, v36, v28, s4
	v_or_b32_e32 v36, s8, v89
	v_perm_b32 v24, v29, v24, s4
	v_perm_b32 v29, v38, v37, s4
	v_ashrrev_i32_e32 v37, 31, v36
	v_lshlrev_b64 v[36:37], 12, v[36:37]
	s_lshl_b32 s9, s2, 9
	v_lshl_or_b32 v36, v32, 8, v36
	v_or3_b32 v32, v33, s9, v32
	v_ashrrev_i32_e32 v33, 31, v32
	v_lshl_add_u64 v[32:33], v[32:33], 2, v[80:81]
	v_perm_b32 v9, v91, v79, s4
	global_load_dword v91, v[32:33], off
	v_ashrrev_i32_e32 v32, 5, v35
	s_mov_b32 s2, 0xfe03f81
	v_and_b32_e32 v34, 24, v34
	v_mul_hi_i32 v33, v32, s2
	v_lshlrev_b32_e32 v162, 2, v34
	v_lshrrev_b32_e32 v34, 31, v33
	v_ashrrev_i32_e32 v33, 4, v33
	v_add_u32_e32 v34, v33, v34
	v_mul_i32_i24_e32 v33, 0x102, v34
	v_perm_b32 v25, v30, v25, s4
	v_perm_b32 v30, v40, v39, s4
	v_lshl_add_u64 v[38:39], v[4:5], 0, v[36:37]
	v_lshl_add_u64 v[36:37], v[6:7], 0, v[36:37]
	v_sub_u32_e32 v32, v32, v33
	v_perm_b32 v27, v43, v27, s4
	v_perm_b32 v26, v31, v26, s4
	v_perm_b32 v31, v42, v41, s4
	v_lshl_add_u64 v[42:43], v[36:37], 0, v[162:163]
	v_ashrrev_i32_e32 v33, 31, v32
	v_mul_i32_i24_e32 v36, 0x4080, v34
	v_lshlrev_b64 v[32:33], 6, v[32:33]
	v_ashrrev_i32_e32 v37, 31, v36
	v_perm_b32 v18, v64, v50, s4
	v_perm_b32 v17, v48, v23, s4
	v_perm_b32 v16, v22, v21, s4
	v_perm_b32 v23, v66, v65, s4
	v_perm_b32 v22, v51, v49, s4
	v_perm_b32 v21, v47, v46, s4
	v_lshl_add_u64 v[64:65], v[38:39], 0, v[162:163]
	v_lshl_add_u64 v[40:41], v[32:33], 0, v[36:37]
	global_load_dwordx4 v[36:39], v[42:43], off offset:144
	global_load_dwordx4 v[46:49], v[42:43], off offset:128
	s_mov_b32 s2, 0x8000
	v_perm_b32 v10, v95, v93, s4
	v_perm_b32 v14, v94, v92, s4
	v_perm_b32 v20, v45, v20, s4
	v_perm_b32 v11, v100, v98, s4
	v_perm_b32 v15, v99, v97, s4
	v_perm_b32 v19, v67, v19, s4
	v_lshlrev_b32_e32 v35, 5, v35
	v_and_b32_e32 v162, 0x3e0, v35
	v_perm_b32 v8, v71, v69, s4
	v_perm_b32 v12, v70, v68, s4
	v_perm_b32 v13, v90, v78, s4
	v_perm_b32 v52, v53, v52, s4
	v_perm_b32 v53, v55, v54, s4
	v_perm_b32 v54, v63, v61, s4
	v_perm_b32 v55, v87, v85, s4
	s_waitcnt vmcnt(0)
	v_cvt_pk_bf16_f32 v32, v46, v47
	v_cvt_pk_bf16_f32 v33, v48, v49
	v_xor_b32_e32 v45, 0x8000, v33
	v_xor_b32_sdwa v92, s2, v33 dst_sel:DWORD dst_unused:UNUSED_PAD src0_sel:DWORD src1_sel:WORD_1
	v_xor_b32_e32 v93, 0x8000, v32
	v_xor_b32_sdwa v94, s2, v32 dst_sel:DWORD dst_unused:UNUSED_PAD src0_sel:DWORD src1_sel:WORD_1
	v_pk_add_f32 v[32:33], v[36:37], 0 neg_lo:[1,1] neg_hi:[1,1]
	v_perm_b32 v45, v92, v45, s4
	v_cvt_pk_bf16_f32 v46, v32, v33
	v_pk_add_f32 v[32:33], v[38:39], 0 neg_lo:[1,1] neg_hi:[1,1]
	global_load_dwordx4 v[36:39], v[42:43], off offset:16
	global_load_dwordx4 v[48:51], v[42:43], off
	v_cvt_pk_bf16_f32 v47, v32, v33
	s_waitcnt vmcnt(0)
	v_cvt_pk_bf16_f32 v32, v48, v49
	v_cvt_pk_bf16_f32 v33, v50, v51
	v_xor_b32_e32 v95, 0x8000, v33
	v_xor_b32_sdwa v97, s2, v33 dst_sel:DWORD dst_unused:UNUSED_PAD src0_sel:DWORD src1_sel:WORD_1
	v_xor_b32_e32 v98, 0x8000, v32
	v_xor_b32_sdwa v99, s2, v32 dst_sel:DWORD dst_unused:UNUSED_PAD src0_sel:DWORD src1_sel:WORD_1
	v_pk_add_f32 v[32:33], v[36:37], 0 neg_lo:[1,1] neg_hi:[1,1]
	s_nop 0
	v_cvt_pk_bf16_f32 v42, v32, v33
	v_pk_add_f32 v[32:33], v[38:39], 0 neg_lo:[1,1] neg_hi:[1,1]
	global_load_dwordx4 v[48:51], v[64:65], off offset:144
	global_load_dwordx4 v[36:39], v[64:65], off offset:128
	v_cvt_pk_bf16_f32 v43, v32, v33
	s_waitcnt vmcnt(0)
	v_cvt_pk_bf16_f32 v36, v36, v37
	v_cvt_pk_bf16_f32 v37, v38, v39
	v_cvt_pk_bf16_f32 v38, v48, v49
	v_cvt_pk_bf16_f32 v39, v50, v51
	global_load_dwordx4 v[48:51], v[64:65], off offset:16
	s_nop 0
	global_load_dwordx4 v[64:67], v[64:65], off
	s_waitcnt vmcnt(1)
	v_cvt_pk_bf16_f32 v34, v48, v49
	v_mov_b32_e32 v48, v160
	s_waitcnt vmcnt(0)
	v_cvt_pk_bf16_f32 v32, v64, v65
	v_and_or_b32 v40, v48, 63, v40
	v_mad_u64_u32 v[48:49], s[2:3], v40, s97, v[82:83]
	v_mad_i32_i24 v49, v41, s97, v49
	v_lshl_add_u64 v[40:41], v[48:49], 0, v[162:163]
	v_cvt_pk_bf16_f32 v33, v66, v67
	global_load_dwordx4 v[64:67], v[40:41], off offset:3600
	global_load_dwordx4 v[68:71], v[40:41], off offset:3584
	s_movk_i32 s2, 0x3300
	v_mul_lo_u32 v40, v44, s2
	s_mov_b64 s[2:3], 0x1ecc6000
	v_cvt_pk_bf16_f32 v35, v50, v51
	v_add_u32_e32 v90, 0x100, v40
	v_lshl_add_u64 v[78:79], v[2:3], 0, s[2:3]
	v_perm_b32 v44, v94, v93, s4
	v_perm_b32 v40, v99, v98, s4
	v_perm_b32 v41, v97, v95, s4
	v_perm_b32 v48, v57, v56, s4
	v_perm_b32 v49, v59, v58, s4
	v_perm_b32 v50, v62, v60, s4
	v_perm_b32 v51, v86, v84, s4
	s_waitcnt vmcnt(0)

.LBB0_1370:
	s_or_b64 exec, exec, s[2:3]
	v_readlane_b32 s2, v253, 1
	v_readlane_b32 s3, v253, 2
	s_load_dword s3, s[2:3], 0x0
	v_mov_b64_e32 v[56:57], v[64:65]
	v_mov_b64_e32 v[60:61], v[68:69]
	v_mov_b64_e32 v[58:59], v[66:67]
	v_mov_b64_e32 v[62:63], v[70:71]
	s_waitcnt lgkmcnt(0)
	s_add_i32 s2, s3, s95
	s_cmpk_gt_i32 s2, 0xc27
	s_cbranch_scc1 .LBB0_1372
	v_lshl_add_u32 v56, s3, 3, v86
	v_subrev_u32_e32 v60, 128, v56
	v_ashrrev_i32_e32 v56, 5, v60
	s_mov_b32 s3, 0xfe03f81
	v_mul_hi_i32 v57, v56, s3
	v_lshrrev_b32_e32 v58, 31, v57
	v_ashrrev_i32_e32 v57, 4, v57
	v_add_u32_e32 v57, v57, v58
	v_mul_i32_i24_e32 v58, 0x102, v57
	v_sub_u32_e32 v56, v56, v58
	v_mul_hi_i32_i24_e32 v59, 0x4080, v57
	v_mul_i32_i24_e32 v58, 0x4080, v57
	v_ashrrev_i32_e32 v57, 31, v56
	v_lshlrev_b64 v[56:57], 6, v[56:57]
	v_mov_b32_e32 v61, v160
	v_lshl_add_u64 v[56:57], v[58:59], 0, v[56:57]
	s_nop 0
	v_and_or_b32 v56, v61, 63, v56
	v_mad_u64_u32 v[58:59], s[4:5], v56, s97, v[82:83]
	v_mov_b32_e32 v56, v59
	v_mad_u64_u32 v[56:57], s[4:5], v57, s97, v[56:57]
	v_mov_b32_e32 v59, v56
	v_lshlrev_b32_e32 v56, 5, v60
	v_and_b32_e32 v162, 0x3e0, v56
	v_lshl_add_u64 v[60:61], v[58:59], 0, v[162:163]
	global_load_dwordx4 v[56:59], v[60:61], off offset:3600
	s_nop 0
	global_load_dwordx4 v[60:63], v[60:61], off offset:3584

.LBB0_1373:
	v_add_u32_e32 v64, s4, v92
	ds_read_b128 v[64:67], v64
	v_add_u32_e32 v95, 0x1000, v86
	v_add_u32_e32 v97, 0x1800, v86
	s_mov_b32 s3, 0x8100000
	s_waitcnt lgkmcnt(0)
	v_mfma_f32_16x16x32_bf16 v[98:101], v[28:31], v[64:67], 0
	v_mfma_f32_16x16x32_bf16 v[102:105], v[24:27], v[64:67], 0
	s_nop 6
	v_cvt_pk_bf16_f32 v106, v98, v99
	v_cvt_pk_bf16_f32 v107, v100, v101
	v_mfma_f32_16x16x32_bf16 v[98:101], v[20:23], v[64:67], 0
	v_cvt_pk_bf16_f32 v108, v102, v103
	v_cvt_pk_bf16_f32 v109, v104, v105
	v_mfma_f32_16x16x32_bf16 v[102:105], v[16:19], v[64:67], 0
	s_nop 4
	v_cvt_pk_bf16_f32 v98, v98, v99
	v_cvt_pk_bf16_f32 v99, v100, v101
	ds_write2_b64 v95, v[106:107], v[98:99] offset1:4
	v_cvt_pk_bf16_f32 v100, v102, v103
	v_cvt_pk_bf16_f32 v101, v104, v105
	ds_write2_b64 v97, v[108:109], v[100:101] offset0:32 offset1:36
	v_mfma_f32_16x16x32_bf16 v[98:101], v[12:15], v[64:67], 0
	v_mfma_f32_16x16x32_bf16 v[102:105], v[8:11], v[64:67], 0
	s_nop 6
	v_cvt_pk_bf16_f32 v106, v98, v99
	v_cvt_pk_bf16_f32 v107, v100, v101
	v_mfma_f32_16x16x32_bf16 v[98:101], v[48:51], v[64:67], 0
	v_cvt_pk_bf16_f32 v102, v102, v103
	v_cvt_pk_bf16_f32 v103, v104, v105
	v_mfma_f32_16x16x32_bf16 v[64:67], v[52:55], v[64:67], 0
	s_nop 4
	v_cvt_pk_bf16_f32 v98, v98, v99
	v_cvt_pk_bf16_f32 v99, v100, v101
	s_nop 0
	v_cvt_pk_bf16_f32 v64, v64, v65
	v_cvt_pk_bf16_f32 v65, v66, v67
	ds_write2_b64 v95, v[106:107], v[98:99] offset0:8 offset1:12
	ds_write2_b64 v97, v[102:103], v[64:65] offset0:40 offset1:44
	s_waitcnt lgkmcnt(0)
	ds_read_u16 v64, v87 offset:4096
	s_waitcnt lgkmcnt(0)
	v_lshlrev_b32_e32 v66, 16, v64
	ds_read_u16 v64, v87 offset:6400
	s_waitcnt lgkmcnt(0)
	v_lshlrev_b32_e32 v95, 16, v64
	v_pk_mul_f32 v[64:65], v[76:77], v[70:71]
	s_nop 0
	v_sub_f32_e32 v64, v64, v65
	v_add_f32_e32 v64, v64, v66
	v_pk_mul_f32 v[66:67], v[84:85], v[70:71]
	s_nop 0
	v_add_f32_e32 v65, v66, v67
	v_add_f32_e32 v66, v65, v95
	v_cvt_pk_bf16_f32 v65, v64, s0
	ds_write_b16 v87, v65 offset:8704
	v_cvt_pk_bf16_f32 v65, v66, s0
	ds_write_b16 v87, v65 offset:8832
	ds_read_u16 v65, v87 offset:4384
	s_waitcnt lgkmcnt(0)
	v_lshlrev_b32_e32 v95, 16, v65
	ds_read_u16 v65, v87 offset:6688
	s_waitcnt lgkmcnt(0)
	v_lshlrev_b32_e32 v97, 16, v65
	ds_read_u16 v65, v87 offset:4240
	ds_read_u16 v67, v87 offset:6544
	s_waitcnt lgkmcnt(1)
	v_lshlrev_b32_e32 v70, 16, v65
	s_waitcnt lgkmcnt(0)
	v_lshlrev_b32_e32 v71, 16, v67
	v_pk_mul_f32 v[66:67], v[84:85], v[66:67] op_sel_hi:[1,0]
	s_nop 0
	v_pk_fma_f32 v[98:99], v[76:77], v[64:65], v[66:67] neg_lo:[0,0,1] neg_hi:[0,0,1]
	v_pk_fma_f32 v[64:65], v[76:77], v[64:65], v[66:67] op_sel_hi:[1,0,1]
	s_nop 0
	v_mov_b32_e32 v99, v65
	v_pk_add_f32 v[64:65], v[98:99], v[70:71]
	s_nop 0
	v_cvt_pk_bf16_f32 v66, v64, s0
	ds_write_b16 v87, v66 offset:8976
	v_cvt_pk_bf16_f32 v66, v65, s0
	ds_write_b16 v87, v66 offset:9104
	v_pk_mul_f32 v[66:67], v[76:77], v[64:65]
	v_pk_mul_f32 v[64:65], v[84:85], v[64:65]
	v_sub_f32_e32 v66, v66, v67
	v_add_f32_e32 v66, v66, v95
	v_add_f32_e32 v64, v64, v65
	v_add_f32_e32 v64, v64, v97
	v_cvt_pk_bf16_f32 v65, v66, s0
	ds_write_b16 v87, v65 offset:9248
	v_cvt_pk_bf16_f32 v65, v64, s0
	ds_write_b16 v87, v65 offset:9376
	ds_read_u16 v65, v87 offset:4672
	s_waitcnt lgkmcnt(0)
	v_lshlrev_b32_e32 v95, 16, v65
	ds_read_u16 v65, v87 offset:6976
	s_waitcnt lgkmcnt(0)
	v_lshlrev_b32_e32 v97, 16, v65
	ds_read_u16 v65, v87 offset:4528
	ds_read_u16 v67, v87 offset:6832
	s_waitcnt lgkmcnt(1)
	v_lshlrev_b32_e32 v70, 16, v65
	v_pk_mul_f32 v[64:65], v[84:85], v[64:65] op_sel_hi:[1,0]
	s_waitcnt lgkmcnt(0)
	v_lshlrev_b32_e32 v71, 16, v67
	v_pk_fma_f32 v[98:99], v[76:77], v[66:67], v[64:65] neg_lo:[0,0,1] neg_hi:[0,0,1]
	v_pk_fma_f32 v[64:65], v[76:77], v[66:67], v[64:65] op_sel_hi:[1,0,1]
	s_nop 0
	v_mov_b32_e32 v99, v65
	v_pk_add_f32 v[64:65], v[98:99], v[70:71]
	s_nop 0
	v_cvt_pk_bf16_f32 v66, v64, s0
	ds_write_b16 v87, v66 offset:9520
	v_cvt_pk_bf16_f32 v66, v65, s0
	ds_write_b16 v87, v66 offset:9648
	v_pk_mul_f32 v[66:67], v[76:77], v[64:65]
	v_pk_mul_f32 v[64:65], v[84:85], v[64:65]
	v_sub_f32_e32 v66, v66, v67
	v_add_f32_e32 v66, v66, v95
	v_add_f32_e32 v64, v64, v65
	v_add_f32_e32 v64, v64, v97
	v_cvt_pk_bf16_f32 v65, v66, s0
	ds_write_b16 v87, v65 offset:9792
	v_cvt_pk_bf16_f32 v65, v64, s0
	ds_write_b16 v87, v65 offset:9920
	ds_read_u16 v65, v87 offset:4960
	s_waitcnt lgkmcnt(0)
	v_lshlrev_b32_e32 v95, 16, v65
	ds_read_u16 v65, v87 offset:7264
	s_waitcnt lgkmcnt(0)
	v_lshlrev_b32_e32 v97, 16, v65
	ds_read_u16 v65, v87 offset:4816
	ds_read_u16 v67, v87 offset:7120
	s_waitcnt lgkmcnt(1)
	v_lshlrev_b32_e32 v70, 16, v65
	v_pk_mul_f32 v[64:65], v[84:85], v[64:65] op_sel_hi:[1,0]
	s_waitcnt lgkmcnt(0)
	v_lshlrev_b32_e32 v71, 16, v67
	v_pk_fma_f32 v[98:99], v[76:77], v[66:67], v[64:65] neg_lo:[0,0,1] neg_hi:[0,0,1]
	v_pk_fma_f32 v[64:65], v[76:77], v[66:67], v[64:65] op_sel_hi:[1,0,1]
	s_nop 0
	v_mov_b32_e32 v99, v65
	v_pk_add_f32 v[64:65], v[98:99], v[70:71]
	s_nop 0
	v_cvt_pk_bf16_f32 v66, v64, s0
	ds_write_b16 v87, v66 offset:10064
	v_cvt_pk_bf16_f32 v66, v65, s0
	ds_write_b16 v87, v66 offset:10192
	v_pk_mul_f32 v[66:67], v[76:77], v[64:65]
	v_pk_mul_f32 v[64:65], v[84:85], v[64:65]
	v_sub_f32_e32 v66, v66, v67
	v_add_f32_e32 v66, v66, v95
	v_add_f32_e32 v64, v64, v65
	v_add_f32_e32 v64, v64, v97
	v_cvt_pk_bf16_f32 v65, v66, s0
	ds_write_b16 v87, v65 offset:10336
	v_cvt_pk_bf16_f32 v65, v64, s0
	ds_write_b16 v87, v65 offset:10464
	ds_read_u16 v65, v87 offset:5248
	s_waitcnt lgkmcnt(0)
	v_lshlrev_b32_e32 v95, 16, v65
	ds_read_u16 v65, v87 offset:7552
	s_waitcnt lgkmcnt(0)
	v_lshlrev_b32_e32 v97, 16, v65
	ds_read_u16 v65, v87 offset:5104
	ds_read_u16 v67, v87 offset:7408
	s_waitcnt lgkmcnt(1)
	v_lshlrev_b32_e32 v70, 16, v65
	v_pk_mul_f32 v[64:65], v[84:85], v[64:65] op_sel_hi:[1,0]
	s_waitcnt lgkmcnt(0)
	v_lshlrev_b32_e32 v71, 16, v67
	v_pk_fma_f32 v[98:99], v[76:77], v[66:67], v[64:65] neg_lo:[0,0,1] neg_hi:[0,0,1]
	v_pk_fma_f32 v[64:65], v[76:77], v[66:67], v[64:65] op_sel_hi:[1,0,1]
	s_nop 0
	v_mov_b32_e32 v99, v65
	v_pk_add_f32 v[64:65], v[98:99], v[70:71]
	s_nop 0
	v_cvt_pk_bf16_f32 v66, v64, s0
	ds_write_b16 v87, v66 offset:10608
	v_cvt_pk_bf16_f32 v66, v65, s0
	ds_write_b16 v87, v66 offset:10736
	v_pk_mul_f32 v[66:67], v[76:77], v[64:65]
	v_pk_mul_f32 v[64:65], v[84:85], v[64:65]
	v_sub_f32_e32 v66, v66, v67
	v_add_f32_e32 v66, v66, v95
	v_add_f32_e32 v64, v64, v65
	v_add_f32_e32 v64, v64, v97
	v_cvt_pk_bf16_f32 v65, v66, s0
	ds_write_b16 v87, v65 offset:10880
	v_cvt_pk_bf16_f32 v65, v64, s0
	ds_write_b16 v87, v65 offset:11008
	ds_read_u16 v65, v87 offset:5536
	s_waitcnt lgkmcnt(0)
	v_lshlrev_b32_e32 v95, 16, v65
	ds_read_u16 v65, v87 offset:7840
	s_waitcnt lgkmcnt(0)
	v_lshlrev_b32_e32 v97, 16, v65
	ds_read_u16 v65, v87 offset:5392
	ds_read_u16 v67, v87 offset:7696
	s_waitcnt lgkmcnt(1)
	v_lshlrev_b32_e32 v70, 16, v65
	v_pk_mul_f32 v[64:65], v[84:85], v[64:65] op_sel_hi:[1,0]
	s_waitcnt lgkmcnt(0)
	v_lshlrev_b32_e32 v71, 16, v67
	v_pk_fma_f32 v[98:99], v[76:77], v[66:67], v[64:65] neg_lo:[0,0,1] neg_hi:[0,0,1]
	v_pk_fma_f32 v[64:65], v[76:77], v[66:67], v[64:65] op_sel_hi:[1,0,1]
	s_nop 0
	v_mov_b32_e32 v99, v65
	v_pk_add_f32 v[64:65], v[98:99], v[70:71]
	s_nop 0
	v_cvt_pk_bf16_f32 v66, v64, s0
	ds_write_b16 v87, v66 offset:11152
	v_cvt_pk_bf16_f32 v66, v65, s0
	ds_write_b16 v87, v66 offset:11280
	v_pk_mul_f32 v[66:67], v[76:77], v[64:65]
	v_pk_mul_f32 v[64:65], v[84:85], v[64:65]
	v_sub_f32_e32 v66, v66, v67
	v_add_f32_e32 v66, v66, v95
	v_add_f32_e32 v64, v64, v65
	v_add_f32_e32 v64, v64, v97
	v_cvt_pk_bf16_f32 v65, v66, s0
	ds_write_b16 v87, v65 offset:11424
	v_cvt_pk_bf16_f32 v65, v64, s0
	ds_write_b16 v87, v65 offset:11552
	ds_read_u16 v65, v87 offset:5824
	s_waitcnt lgkmcnt(0)
	v_lshlrev_b32_e32 v95, 16, v65
	ds_read_u16 v65, v87 offset:8128
	s_waitcnt lgkmcnt(0)
	v_lshlrev_b32_e32 v97, 16, v65
	ds_read_u16 v65, v87 offset:5680
	ds_read_u16 v67, v87 offset:7984
	s_waitcnt lgkmcnt(1)
	v_lshlrev_b32_e32 v70, 16, v65
	v_pk_mul_f32 v[64:65], v[84:85], v[64:65] op_sel_hi:[1,0]
	s_waitcnt lgkmcnt(0)
	v_lshlrev_b32_e32 v71, 16, v67
	v_pk_fma_f32 v[98:99], v[76:77], v[66:67], v[64:65] neg_lo:[0,0,1] neg_hi:[0,0,1]
	v_pk_fma_f32 v[64:65], v[76:77], v[66:67], v[64:65] op_sel_hi:[1,0,1]
	s_nop 0
	v_mov_b32_e32 v99, v65
	v_pk_add_f32 v[64:65], v[98:99], v[70:71]
	s_nop 0
	v_cvt_pk_bf16_f32 v66, v64, s0
	ds_write_b16 v87, v66 offset:11696
	v_cvt_pk_bf16_f32 v66, v65, s0
	ds_write_b16 v87, v66 offset:11824
	v_pk_mul_f32 v[66:67], v[76:77], v[64:65]
	v_pk_mul_f32 v[64:65], v[84:85], v[64:65]
	v_sub_f32_e32 v66, v66, v67
	v_add_f32_e32 v66, v66, v95
	v_add_f32_e32 v64, v64, v65
	v_add_f32_e32 v64, v64, v97
	v_cvt_pk_bf16_f32 v65, v66, s0
	ds_write_b16 v87, v65 offset:11968
	v_cvt_pk_bf16_f32 v65, v64, s0
	ds_write_b16 v87, v65 offset:12096
	ds_read_u16 v65, v87 offset:6112
	s_waitcnt lgkmcnt(0)
	v_lshlrev_b32_e32 v95, 16, v65
	ds_read_u16 v65, v87 offset:8416
	s_waitcnt lgkmcnt(0)
	v_lshlrev_b32_e32 v97, 16, v65
	ds_read_u16 v65, v87 offset:5968
	ds_read_u16 v67, v87 offset:8272
	s_waitcnt lgkmcnt(1)
	v_lshlrev_b32_e32 v70, 16, v65
	v_pk_mul_f32 v[64:65], v[84:85], v[64:65] op_sel_hi:[1,0]
	s_waitcnt lgkmcnt(0)
	v_lshlrev_b32_e32 v71, 16, v67
	v_pk_fma_f32 v[98:99], v[76:77], v[66:67], v[64:65] neg_lo:[0,0,1] neg_hi:[0,0,1]
	v_pk_fma_f32 v[64:65], v[76:77], v[66:67], v[64:65] op_sel_hi:[1,0,1]
	s_nop 0
	v_mov_b32_e32 v99, v65
	v_pk_add_f32 v[64:65], v[98:99], v[70:71]
	s_nop 0
	v_cvt_pk_bf16_f32 v66, v64, s0
	ds_write_b16 v87, v66 offset:12240
	v_cvt_pk_bf16_f32 v66, v65, s0
	ds_write_b16 v87, v66 offset:12368
	v_pk_mul_f32 v[66:67], v[76:77], v[64:65]
	v_pk_mul_f32 v[64:65], v[84:85], v[64:65]
	v_sub_f32_e32 v66, v66, v67
	v_add_f32_e32 v66, v66, v95
	v_add_f32_e32 v64, v64, v65
	v_add_f32_e32 v64, v64, v97
	v_cvt_pk_bf16_f32 v65, v66, s0
	ds_write_b16 v87, v65 offset:12512
	v_cvt_pk_bf16_f32 v65, v64, s0
	ds_write_b16 v87, v65 offset:12640
	ds_read_u16 v65, v87 offset:6256
	ds_read_u16 v67, v87 offset:8560
	v_add_u32_e32 v95, s4, v93
	s_addk_i32 s4, 0x400
	s_waitcnt lgkmcnt(1)
	v_lshlrev_b32_e32 v70, 16, v65
	v_pk_mul_f32 v[64:65], v[84:85], v[64:65] op_sel_hi:[1,0]
	s_waitcnt lgkmcnt(0)
	v_lshlrev_b32_e32 v71, 16, v67
	v_pk_fma_f32 v[98:99], v[76:77], v[66:67], v[64:65] neg_lo:[0,0,1] neg_hi:[0,0,1]
	v_pk_fma_f32 v[64:65], v[76:77], v[66:67], v[64:65] op_sel_hi:[1,0,1]
	s_nop 0
	v_mov_b32_e32 v99, v65
	v_pk_add_f32 v[70:71], v[98:99], v[70:71]
	s_nop 0
	v_cvt_pk_bf16_f32 v64, v70, s0
	ds_write_b16 v87, v64 offset:12784
	v_cvt_pk_bf16_f32 v64, v71, s0
	ds_write_b16 v87, v64 offset:12912
	s_waitcnt lgkmcnt(0)
	ds_read_b128 v[64:67], v94 offset:8704
	ds_read_b128 v[98:101], v94 offset:8768
	s_waitcnt lgkmcnt(1)
	v_mfma_f32_16x16x32_bf16 v[64:67], v[64:67], v[32:35], 0
	ds_read_u16 v97, v95
	s_waitcnt lgkmcnt(0)
	v_lshlrev_b32_e32 v97, 16, v97
	v_mfma_f32_16x16x32_bf16 v[64:67], v[98:101], v[36:39], v[64:67]
	ds_read_b128 v[98:101], v94 offset:8832
	s_waitcnt lgkmcnt(0)
	v_mfma_f32_16x16x32_bf16 v[64:67], v[98:101], v[40:43], v[64:67]
	ds_read_b128 v[98:101], v94 offset:8896
	s_waitcnt lgkmcnt(0)
	v_mfma_f32_16x16x32_bf16 v[64:67], v[98:101], v[44:47], v[64:67]
	v_lshl_add_u64 v[98:99], v[68:69], 0, s[6:7]
	v_add_co_u32_e32 v98, vcc, s3, v98
	s_nop 5
	v_fma_f32 v64, v91, v97, v64
	v_mul_f32_e32 v97, 0x3d372713, v64
	v_mul_f32_e32 v97, v64, v97
	v_fma_f32 v97, v64, v97, v64
	v_mul_f32_e32 v97, 0x3f4c422a, v97
	v_add_f32_e32 v97, v97, v97
	v_mul_f32_e32 v97, 0x3fb8aa3b, v97
	v_exp_f32_e32 v97, v97
	v_mul_f32_e32 v64, 0.5, v64
	v_addc_co_u32_e32 v99, vcc, 0, v99, vcc
	v_add_f32_e32 v97, 1.0, v97
	v_rcp_f32_e32 v97, v97
	s_add_u32 s6, s6, 0x4000
	s_addc_u32 s7, s7, 0
	s_cmpk_lg_i32 s4, 0x1000
	v_fma_f32 v97, v97, -2.0, 1.0
	v_add_f32_e32 v97, 1.0, v97
	v_mul_f32_e32 v64, v64, v97
	v_cvt_pk_bf16_f32 v64, v64, s0
	global_store_short v[98:99], v64, off
	ds_read_u16 v64, v95 offset:64
	s_waitcnt lgkmcnt(0)
	v_lshlrev_b32_e32 v64, 16, v64
	v_fma_f32 v64, v91, v64, v65
	v_mul_f32_e32 v65, 0x3d372713, v64
	v_mul_f32_e32 v65, v64, v65
	v_fma_f32 v65, v64, v65, v64
	v_mul_f32_e32 v65, 0x3f4c422a, v65
	v_add_f32_e32 v65, v65, v65
	v_mul_f32_e32 v65, 0x3fb8aa3b, v65
	v_exp_f32_e32 v65, v65
	v_mul_f32_e32 v64, 0.5, v64
	v_add_f32_e32 v65, 1.0, v65
	v_rcp_f32_e32 v65, v65
	s_nop 0
	v_fma_f32 v65, v65, -2.0, 1.0
	v_add_f32_e32 v65, 1.0, v65
	v_mul_f32_e32 v64, v64, v65
	v_cvt_pk_bf16_f32 v64, v64, s0
	global_store_short v[98:99], v64, off offset:1024
	ds_read_u16 v64, v95 offset:128
	s_waitcnt lgkmcnt(0)
	v_lshlrev_b32_e32 v64, 16, v64
	v_fma_f32 v64, v91, v64, v66
	v_mul_f32_e32 v65, 0x3d372713, v64
	v_mul_f32_e32 v65, v64, v65
	v_fma_f32 v65, v64, v65, v64
	v_mul_f32_e32 v65, 0x3f4c422a, v65
	v_add_f32_e32 v65, v65, v65
	v_mul_f32_e32 v65, 0x3fb8aa3b, v65
	v_exp_f32_e32 v65, v65
	v_mul_f32_e32 v64, 0.5, v64
	v_add_f32_e32 v65, 1.0, v65
	v_rcp_f32_e32 v65, v65
	s_nop 0
	v_fma_f32 v65, v65, -2.0, 1.0
	v_add_f32_e32 v65, 1.0, v65
	v_mul_f32_e32 v64, v64, v65
	v_cvt_pk_bf16_f32 v64, v64, s0
	global_store_short v[98:99], v64, off offset:2048
	ds_read_u16 v64, v95 offset:192
	s_waitcnt lgkmcnt(0)
	v_lshlrev_b32_e32 v64, 16, v64
	v_fmac_f32_e32 v67, v91, v64
	v_mul_f32_e32 v64, 0x3d372713, v67
	v_mul_f32_e32 v64, v67, v64
	v_fma_f32 v64, v67, v64, v67
	v_mul_f32_e32 v64, 0x3f4c422a, v64
	v_add_f32_e32 v64, v64, v64
	v_mul_f32_e32 v64, 0x3fb8aa3b, v64
	v_exp_f32_e32 v64, v64
	v_mul_f32_e32 v65, 0.5, v67
	v_add_f32_e32 v64, 1.0, v64
	v_rcp_f32_e32 v64, v64
	s_nop 0
	v_fma_f32 v64, v64, -2.0, 1.0
	v_add_f32_e32 v64, 1.0, v64
	v_mul_f32_e32 v64, v65, v64
	v_cvt_pk_bf16_f32 v64, v64, s0
	global_store_short v[98:99], v64, off offset:3072
	s_waitcnt lgkmcnt(0)
	s_cbranch_scc1 .LBB0_1373
	s_add_i32 s95, s2, -16
	v_mov_b64_e32 v[70:71], v[62:63]
	v_mov_b64_e32 v[66:67], v[58:59]
	s_cmpk_lt_i32 s95, 0xc18
	v_mov_b64_e32 v[68:69], v[60:61]
	v_mov_b64_e32 v[64:65], v[56:57]
	s_cbranch_scc1 .LBB0_1240
